# plus prep phase token body: all independent loads of a token issued together at the top, consumed by register copies
# speedup vs baseline: 1.0588x; 1.0032x over previous
; __global__ void __launch_bounds__(NTHR) fwd_kernel(Args args) {
;     ...
;                 const bf16* zr = Z1 + (size_t)t * 1024;
;                 { const u32x4 kv = *(const u32x4*)((const bf16*)(ws + WS_Z2) + (size_t)t * 1024 + 512 + 8 * lane); float ss = 0.f;
; #pragma unroll
;                   for (int e = 0; e < 4; ++e) { const float x = bf_lo(kv[e]), y = bf_hi(kv[e]); ss += x * x + y * y; }
;                   ss += __shfl_xor(ss, 1); ss += __shfl_xor(ss, 2);
;                   if (t < SEQ) kmx0 = fmaxf(kmx0, ss); else kmx1 = fmaxf(kmx1, ss); }
;                 { const u32x2 v = ((const u32x2*)zr)[lane]; float x0 = bf_lo(v.x), x1 = bf_hi(v.x), x2 = bf_lo(v.y), x3 = bf_hi(v.y);
;                   const float rs = __builtin_amdgcn_rsqf(wave_sum(x0 * x0 + x1 * x1 + x2 * x2 + x3 * x3) * (1.0f / 256.0f) + 1e-6f); const f32x4 gq = ((const f32x4*)q_norm)[lane];
;                   u32x2 o; o.x = cvt_pk_bf16(x0 * rs * gq.x, x1 * rs * gq.y); o.y = cvt_pk_bf16(x2 * rs * gq.z, x3 * rs * gq.w); ((u32x2*)(CQN + (size_t)t * 256))[lane] = o; }
;                 { const unsigned v = ((const unsigned*)(zr + 256))[lane]; float x0 = bf_lo(v), x1 = bf_hi(v);
;                   const float rs = __builtin_amdgcn_rsqf(wave_sum(x0 * x0 + x1 * x1) * (1.0f / 128.0f) + 1e-6f);
;                   ((unsigned*)(CKVN + (size_t)t * 128))[lane] = cvt_pk_bf16(x0 * rs * kv_norm[2 * lane], x1 * rs * kv_norm[2 * lane + 1]); }
;                 if (lane < 16) { const float x1 = bf_lo((unsigned)zr[384 + lane]), x2 = bf_lo((unsigned)zr[400 + lane]); float s, c; sincos_acc((float)pos[t] * ((const float*)(ws + WS_TAB))[lane], s, c);
;                   KR[(size_t)t * 32 + lane] = (bf16)(cvt_pk_bf16(x1 * c - x2 * s, 0.f) & 0xffffu); KR[(size_t)t * 32 + 16 + lane] = (bf16)(cvt_pk_bf16(x2 * c + x1 * s, 0.f) & 0xffffu); }
;                 { const int tp = t & (SEQ - 1), wdw = 2 << (lane >> 4), cnt = (tp + 1) < wdw ? (tp + 1) : wdw;
;                   float a[8]; const u32x4 cur = *(const u32x4*)(zr + 512 + 8 * lane);
; #pragma unroll
;                   for (int e = 0; e < 4; ++e) { a[2 * e] = bf_lo(cur[e]); a[2 * e + 1] = bf_hi(cur[e]); }
;                   float sm[8];
; #pragma unroll
;                   for (int e = 0; e < 8; ++e) sm[e] = a[e];
;                   for (int j = 1; j < cnt; ++j) { const u32x4 pv = *(const u32x4*)(zr - (size_t)j * 1024 + 512 + 8 * lane);
; #pragma unroll
.LBB0_461:
	s_ashr_i32 s43, s42, 31
	s_lshl_b64 s[44:45], s[42:43], 11
	s_add_u32 s18, s72, s44
	s_addc_u32 s19, s73, s45
	v_lshlrev_b32_e32 v2, 1, v0
	v_lshl_add_u64 v[26:27], s[18:19], 0, v[2:3]
	s_mov_b32 s12, 0x7400000
	v_add_co_u32_e32 v26, vcc, s12, v26
	s_add_u32 s44, s4, s44
	s_nop 0
	v_addc_co_u32_e32 v27, vcc, 0, v27, vcc
	flat_load_dwordx4 v[26:29], v[26:27] offset:1024
	s_addc_u32 s45, s5, s45
	v_mov_b32_e32 v144, v24
	v_mov_b32_e32 v145, v3
	v_lshl_add_u64 v[138:139], s[44:45], 0, v[144:145]
	global_load_dwordx2 v[124:125], v[138:139], off
	global_load_dwordx4 v[128:131], v[4:5], off
	v_lshl_add_u64 v[146:147], v[138:139], 0, v[18:19]
	global_load_dword v126, v[146:147], off offset:512
	global_load_dwordx2 v[132:133], v[8:9], off
	v_lshl_add_u64 v[150:151], s[44:45], 0, v[2:3]
	global_load_dwordx4 v[140:143], v[150:151], off offset:1024
	v_lshl_add_u64 v[148:149], v[146:147], 0, v[20:21]
	s_lshl_b64 s[98:99], s[42:43], 2
	s_add_u32 s98, s36, s98
	s_addc_u32 s99, s37, s99
	s_and_saveexec_b64 s[46:47], s[40:41]
	global_load_ushort v134, v[148:149], off offset:768
	global_load_ushort v135, v[148:149], off offset:800
	global_load_dword v136, v[12:13], off
	global_load_dword v137, v3, s[98:99]
	s_or_b64 exec, exec, s[46:47]
	s_lshl_b64 s[18:19], s[42:43], 9
	s_waitcnt vmcnt(0) lgkmcnt(0)
	v_lshlrev_b32_e32 v31, 16, v27
	v_lshlrev_b32_e32 v30, 16, v26
	v_and_b32_e32 v27, 0xffff0000, v27
	v_and_b32_e32 v26, 0xffff0000, v26
	v_pk_mul_f32 v[26:27], v[26:27], v[26:27]
	s_nop 0
	v_pk_fma_f32 v[26:27], v[30:31], v[30:31], v[26:27]
	v_lshlrev_b32_e32 v31, 16, v29
	v_lshlrev_b32_e32 v30, 16, v28
	v_and_b32_e32 v29, 0xffff0000, v29
	v_and_b32_e32 v28, 0xffff0000, v28
	v_pk_mul_f32 v[28:29], v[28:29], v[28:29]
	v_add_f32_e32 v25, v26, v27
	v_pk_fma_f32 v[28:29], v[30:31], v[30:31], v[28:29]
	s_nop 0
	v_add_f32_e32 v25, v25, v28
	v_add_f32_e32 v25, v25, v29
	ds_bpermute_b32 v26, v44, v25
	s_waitcnt lgkmcnt(0)
	v_add_f32_e32 v52, v25, v26
	v_mov_b32_e32 v25, v3
	v_lshl_add_u64 v[30:31], s[44:45], 0, v[24:25]
	v_mov_b32_e32 v32, v124
	v_mov_b32_e32 v33, v125
	v_mov_b32_e32 v26, v128
	v_mov_b32_e32 v27, v129
	v_mov_b32_e32 v28, v130
	v_mov_b32_e32 v29, v131
	ds_bpermute_b32 v53, v45, v52
	s_waitcnt lgkmcnt(0)
	v_lshlrev_b32_e32 v38, 16, v32
	v_and_b32_e32 v39, 0xffff0000, v32
	v_lshlrev_b32_e32 v34, 16, v33
	v_and_b32_e32 v35, 0xffff0000, v33
	v_pk_mul_f32 v[32:33], v[38:39], v[38:39]
	v_pk_mul_f32 v[36:37], v[34:35], v[34:35]
	v_add_f32_e32 v25, v32, v33
	v_add_f32_e32 v25, v36, v25
	v_add_f32_e32 v25, v37, v25
	ds_bpermute_b32 v32, v44, v25
	s_waitcnt lgkmcnt(0)
	v_add_f32_e32 v25, v25, v32
	ds_bpermute_b32 v32, v45, v25
	s_waitcnt lgkmcnt(0)
	v_add_f32_e32 v25, v25, v32
	ds_bpermute_b32 v32, v46, v25
	s_waitcnt lgkmcnt(0)
	v_add_f32_e32 v25, v25, v32
	ds_bpermute_b32 v32, v47, v25
	s_waitcnt lgkmcnt(0)
	v_add_f32_e32 v25, v25, v32
	ds_bpermute_b32 v32, v48, v25
	s_waitcnt lgkmcnt(0)
	v_add_f32_e32 v25, v25, v32
	ds_bpermute_b32 v32, v49, v25
	s_waitcnt lgkmcnt(0)
	v_add_f32_e32 v25, v25, v32
	v_fmamk_f32 v25, v25, 0x3b800000, v212
	v_rsq_f32_e32 v32, v25
	s_nop 0
	v_pk_mul_f32 v[36:37], v[32:33], v[38:39] op_sel_hi:[0,1]
	v_pk_mul_f32 v[32:33], v[32:33], v[34:35] op_sel_hi:[0,1]
	v_pk_mul_f32 v[26:27], v[26:27], v[36:37]
	v_pk_mul_f32 v[28:29], v[28:29], v[32:33]
	v_cvt_pk_bf16_f32 v26, v26, v27
	v_cvt_pk_bf16_f32 v27, v28, v29
	v_lshl_add_u64 v[28:29], v[6:7], 0, s[18:19]
	global_store_dwordx2 v[28:29], v[26:27], off
	v_lshl_add_u64 v[26:27], v[30:31], 0, v[18:19]
	v_mov_b32_e32 v25, v126
	s_lshl_b64 s[18:19], s[42:43], 8
	s_waitcnt lgkmcnt(0)
	v_lshlrev_b32_e32 v28, 16, v25
	v_and_b32_e32 v29, 0xffff0000, v25
	v_pk_mul_f32 v[30:31], v[28:29], v[28:29]
	s_nop 0
	v_add_f32_e32 v25, v30, v31
	ds_bpermute_b32 v30, v44, v25
	s_waitcnt lgkmcnt(0)
	v_add_f32_e32 v25, v25, v30
	ds_bpermute_b32 v30, v45, v25
	s_waitcnt lgkmcnt(0)
	v_add_f32_e32 v25, v25, v30
	ds_bpermute_b32 v30, v46, v25
	s_waitcnt lgkmcnt(0)
	v_add_f32_e32 v25, v25, v30
	ds_bpermute_b32 v30, v47, v25
	s_waitcnt lgkmcnt(0)
	v_add_f32_e32 v25, v25, v30
	ds_bpermute_b32 v30, v48, v25
	s_waitcnt lgkmcnt(0)
	v_add_f32_e32 v25, v25, v30
	ds_bpermute_b32 v30, v49, v25
	s_waitcnt lgkmcnt(0)
	v_add_f32_e32 v25, v25, v30
	v_fmamk_f32 v25, v25, 0x3c000000, v212
	v_rsq_f32_e32 v30, v25
	s_nop 0
	v_pk_mul_f32 v[28:29], v[30:31], v[28:29] op_sel_hi:[0,1]
	v_mov_b32_e32 v30, v132
	v_mov_b32_e32 v31, v133
	v_pk_mul_f32 v[28:29], v[30:31], v[28:29]
	s_nop 0
	v_cvt_pk_bf16_f32 v25, v28, v29
	v_lshl_add_u64 v[28:29], v[10:11], 0, s[18:19]
	global_store_dword v[28:29], v25, off
	s_and_saveexec_b64 s[46:47], s[40:41]
	s_cbranch_execz .LBB0_463
	v_lshl_add_u64 v[26:27], v[26:27], 0, v[20:21]
	v_mov_b32_e32 v25, v134
	s_lshl_b64 s[18:19], s[42:43], 2
	v_mov_b32_e32 v26, v135
	s_add_u32 s18, s36, s18
	s_addc_u32 s19, s37, s19
	v_mov_b32_e32 v27, v136
	s_waitcnt lgkmcnt(0)
	v_lshlrev_b32_e32 v25, 16, v25
	v_lshlrev_b32_e32 v30, 16, v26
	v_mov_b32_e32 v26, v137
	s_mov_b32 s18, 0x6dc9c883
	s_mov_b32 s19, 0x3fc45f30
	v_cvt_f32_i32_e32 v26, v26
	v_mul_f32_e32 v26, v27, v26
	v_cvt_f64_f32_e32 v[26:27], v26
	v_mul_f64 v[28:29], v[26:27], s[18:19]
	v_rndne_f64_e32 v[28:29], v[28:29]
	v_fma_f64 v[26:27], v[26:27], s[18:19], -v[28:29]
	v_cvt_f32_f64_e32 v26, v[26:27]
	v_sin_f32_e32 v28, v26
	v_cos_f32_e32 v29, v26
	s_lshl_b64 s[18:19], s[42:43], 6
	v_mul_f32_e32 v26, v28, v30
	v_fma_f32 v26, v29, v25, -v26
	v_mul_f32_e32 v25, v28, v25
	v_fmac_f32_e32 v25, v29, v30
	v_cvt_pk_bf16_f32 v31, v26, s0
	v_lshl_add_u64 v[26:27], v[14:15], 0, s[18:19]
	v_cvt_pk_bf16_f32 v25, v25, s0
	global_store_short v[26:27], v31, off
	global_store_short v[26:27], v25, off offset:32
.LBB0_463:
	s_or_b64 exec, exec, s[46:47]
	v_lshl_add_u64 v[26:27], s[44:45], 0, v[2:3]
	v_mov_b32_e32 v38, v140
	v_mov_b32_e32 v39, v141
	v_mov_b32_e32 v40, v142
	v_mov_b32_e32 v41, v143
	s_and_b32 s12, s42, 0x1fff
	s_cmp_eq_u32 s12, 0
	s_waitcnt lgkmcnt(0)
	v_lshlrev_b32_e32 v34, 16, v38
	v_and_b32_e32 v37, 0xffff0000, v38
	v_lshlrev_b32_e32 v30, 16, v39
	v_and_b32_e32 v33, 0xffff0000, v39
	v_lshlrev_b32_e32 v28, 16, v40
	v_and_b32_e32 v29, 0xffff0000, v40
	v_lshlrev_b32_e32 v26, 16, v41
	v_and_b32_e32 v27, 0xffff0000, v41
	v_mov_b32_e32 v35, v37
	v_mov_b32_e32 v36, v34
	v_mov_b32_e32 v31, v33
	v_mov_b32_e32 v32, v30
	v_mov_b32_e32 v38, v28
	v_mov_b32_e32 v39, v29
	s_cbranch_scc1 .LBB0_459
	s_and_b32 s15, s6, 0x1fff
	s_add_i32 s15, s15, 1
	v_min_u32_e32 v2, s15, v1
	v_max_u32_e32 v2, 2, v2
	v_add_u32_e32 v2, -1, v2
	s_mov_b64 s[44:45], 0
	v_mov_b64_e32 v[42:43], v[22:23]
	v_mov_b64_e32 v[40:41], v[26:27]
